# final out-projection epilogue: the 16 bf16 residual-tile loads are issued at the top of the epilogue (4 destinations renamed to free VGPRs), before the modulation-vector loads and the divisions
# speedup vs baseline: 1.0272x; 1.0037x over previous
.LBB0_1513:
	s_lshl_b32 s42, s10, 6
	s_lshl_b32 s13, s10, 13
	s_lshl_b32 s10, s75, 5
	s_and_b32 s43, s10, 0x60
	s_mov_b64 s[10:11], 0x80
	s_add_i32 m0, s36, 0x18000
	v_lshl_add_u64 v[6:7], v[6:7], 0, s[10:11]
	s_lshr_b32 s16, s43, 3
	s_waitcnt vmcnt(2)
	s_barrier
	global_load_lds_dwordx4 v[6:7], off
	v_lshl_add_u64 v[4:5], v[4:5], 0, s[10:11]
	s_add_i32 m0, s36, 0x1a000
	s_add_i32 s44, s36, 0x8000
	s_add_i32 s45, s36, 0xa000
	global_load_lds_dwordx4 v[4:5], off
	v_lshl_add_u64 v[0:1], v[0:1], 0, s[10:11]
	s_mov_b32 m0, s44
	s_add_u32 s14, s6, 0x40080
	global_load_lds_dwordx4 v[0:1], off
	v_lshl_add_u64 v[0:1], v[2:3], 0, s[10:11]
	s_mov_b32 m0, s45
	s_addc_u32 s15, s7, 0
	global_load_lds_dwordx4 v[0:1], off
	s_add_i32 m0, s36, 0x1c000
	v_lshl_add_u64 v[0:1], s[14:15], 0, v[212:213]
	global_load_lds_dwordx4 v[0:1], off
	v_lshl_add_u64 v[0:1], s[14:15], 0, v[208:209]
	s_add_i32 m0, s36, 0x1e000
	s_sext_i32_i8 s31, s12
	global_load_lds_dwordx4 v[0:1], off
	v_and_b32_e32 v1, 48, v9
	v_lshlrev_b32_e32 v3, 6, v9
	s_movk_i32 s12, 0x3c0
	v_ashrrev_i32_e32 v0, 6, v9
	v_and_or_b32 v1, v3, s12, v1
	v_lshlrev_b32_e32 v3, 2, v9
	v_lshl_add_u32 v2, v0, 10, s13
	v_and_b32_e32 v3, 32, v3
	v_add_lshl_u32 v0, v0, s16, 10
	v_bitop3_b32 v245, v1, v0, v3 bitop3:0xde
	v_lshlrev_b32_e32 v0, 14, v8
	v_and_b32_e32 v0, 0xffff8000, v0
	v_bitop3_b32 v2, v1, v2, v3 bitop3:0xde
	v_lshl_add_u32 v0, v10, 11, v0
	v_and_b32_e32 v1, 1, v8
	v_lshl_or_b32 v0, v1, 6, v0
	v_lshl_add_u32 v216, v11, 1, v0
	v_lshlrev_b32_e32 v0, 14, v12
	v_and_b32_e32 v0, 0xffff8000, v0
	s_waitcnt vmcnt(6)
	s_cmpk_lt_u32 s74, 0x100
	v_lshl_add_u32 v0, v13, 11, v0
	v_and_b32_e32 v1, 1, v12
	s_cselect_b64 s[12:13], -1, 0
	v_lshl_or_b32 v0, v1, 6, v0
	s_add_i32 s48, 0, 0x10000
	s_add_i32 s49, 0, 0x14000
	s_mov_b32 s46, 0x18000
	s_mov_b32 s47, 0x8000
	v_mov_b32_e32 v217, v213
	v_lshl_add_u32 v218, v14, 1, v0
	v_mov_b32_e32 v219, v213
	v_add_u32_e32 v246, s48, v245
	v_add_u32_e32 v247, s49, v245
	v_add_u32_e32 v248, 0, v2
	s_mov_b64 s[14:15], 0x102000
	s_mov_b32 s50, 0x102000
	s_mov_b64 s[16:17], 0x1000
	s_movk_i32 s51, 0x1000
	s_mov_b64 s[18:19], 0x101000
	s_mov_b32 s52, 0x101000
	s_mov_b32 s53, 0x21800000
	s_mov_b64 s[20:21], 0x1800000
	s_mov_b32 s54, 0x20000
	s_mov_b32 s55, 0x30000
	s_mov_b32 s56, 0x90000
	s_mov_b32 s57, 0xa0000
	s_mov_b32 s58, 0xb0000
	v_mov_b32_e32 v253, 0x5d800000
	s_mov_b64 s[26:27], s[6:7]
	s_mov_b64 s[24:25], s[4:5]
	s_barrier
	s_branch .LBB0_1516

.LBB0_1522:
	v_mov_b32_e32 v162, v244
	s_mov_b64 s[60:61], s[0:1]
	s_lshl_b32 s23, s31, 8
	v_ashrrev_i32_e32 v128, 1, v162
	s_load_dwordx4 s[4:7], s[60:61], 0xa0
	s_ashr_i32 s62, s30, 3
	s_or_b32 s23, s23, s43
	v_and_b32_e32 v128, -8, v128
	s_ashr_i32 s63, s62, 31
	v_add_u32_e32 v160, s23, v128
	s_mul_i32 s23, s62, 0xc00
	s_lshl_b64 s[34:35], s[62:63], 22
	s_add_i32 s62, s23, 0x6c00
	s_ashr_i32 s63, s62, 31
	s_load_dwordx2 s[60:61], s[60:61], 0x20
	s_lshl_b64 s[62:63], s[62:63], 2
	s_waitcnt lgkmcnt(0)
	s_add_u32 s62, s6, s62
	v_ashrrev_i32_e32 v161, 31, v160
	s_addc_u32 s63, s7, s63
	v_lshlrev_b64 v[228:229], 2, v[160:161]
	s_add_u32 s6, s6, s34
	s_addc_u32 s7, s7, s35
	s_ashr_i32 s31, s30, 31
	s_lshl_b64 s[30:31], s[30:31], 8
	s_add_u32 s23, s30, s42
	s_addc_u32 s30, s31, 0
	v_and_or_b32 v242, v162, 15, s23
	v_mov_b32_e32 v243, s30
	v_lshl_add_u64 v[238:239], v[242:243], 0, s[10:11]
	v_lshlrev_b64 v[146:147], 11, v[242:243]
	v_lshl_add_u64 v[144:145], v[160:161], 1, s[6:7]
	v_lshl_add_u64 v[144:145], v[144:145], 0, s[20:21]
	v_lshl_add_u64 v[146:147], v[144:145], 0, v[146:147]
	v_add_co_u32_e32 v148, vcc, s47, v146
	global_load_dwordx4 v[204:207], v[146:147], off nt
	global_load_dwordx4 v[200:203], v[146:147], off offset:256 nt
	v_addc_co_u32_e32 v149, vcc, 0, v147, vcc
	global_load_dwordx4 v[196:199], v[148:149], off nt
	global_load_dwordx4 v[192:195], v[148:149], off offset:256 nt
	v_add_co_u32_e32 v148, vcc, s41, v146
	s_nop 1
	v_addc_co_u32_e32 v149, vcc, 0, v147, vcc
	v_add_co_u32_e32 v146, vcc, s46, v146
	global_load_dwordx4 v[188:191], v[148:149], off nt
	global_load_dwordx4 v[184:187], v[148:149], off offset:256 nt
	v_addc_co_u32_e32 v147, vcc, 0, v147, vcc
	global_load_dwordx4 v[180:183], v[146:147], off nt
	global_load_dwordx4 v[176:179], v[146:147], off offset:256 nt
	v_lshlrev_b64 v[146:147], 11, v[238:239]
	v_lshl_add_u64 v[148:149], v[144:145], 0, v[146:147]
	global_load_dwordx4 v[172:175], v[148:149], off nt
	global_load_dwordx4 v[168:171], v[148:149], off offset:256 nt
	v_or_b32_e32 v148, 0x8000, v146
	v_mov_b32_e32 v149, v147
	v_lshl_add_u64 v[148:149], v[144:145], 0, v[148:149]
	global_load_dwordx4 v[164:167], v[148:149], off nt
	global_load_dwordx4 v[160:163], v[148:149], off offset:256 nt
	v_or_b32_e32 v148, 0x10000, v146
	v_mov_b32_e32 v149, v147
	v_or_b32_e32 v146, 0x18000, v146
	v_lshl_add_u64 v[148:149], v[144:145], 0, v[148:149]
	v_lshl_add_u64 v[144:145], v[144:145], 0, v[146:147]
	global_load_dwordx4 v[208:211], v[148:149], off nt
	global_load_dwordx4 v[212:215], v[148:149], off offset:256 nt
	s_nop 0
	global_load_dwordx4 v[216:219], v[144:145], off nt
	s_nop 0
	global_load_dwordx4 v[246:249], v[144:145], off offset:256 nt
	v_lshl_add_u64 v[144:145], s[62:63], 0, v[228:229]
	v_add_co_u32_e32 v128, vcc, s50, v144
	v_lshl_add_u64 v[136:137], s[60:61], 0, v[228:229]
	s_nop 0
	v_addc_co_u32_e32 v129, vcc, 0, v145, vcc
	v_lshl_add_u64 v[148:149], v[136:137], 0, s[16:17]
	v_add_co_u32_e32 v136, vcc, s51, v136
	v_lshl_add_u64 v[154:155], v[144:145], 0, s[14:15]
	s_nop 0
	v_addc_co_u32_e32 v137, vcc, 0, v137, vcc
	v_lshl_add_u64 v[156:157], v[144:145], 0, s[18:19]
	v_add_co_u32_e32 v144, vcc, s52, v144
	global_load_dwordx4 v[132:135], v[128:129], off
	s_nop 0
	global_load_dwordx4 v[128:131], v[154:155], off offset:16
	v_addc_co_u32_e32 v145, vcc, 0, v145, vcc
	global_load_dwordx4 v[136:139], v[136:137], off
	s_nop 0
	global_load_dwordx4 v[140:143], v[148:149], off offset:16
	s_nop 0
	global_load_dwordx4 v[144:147], v[144:145], off
	s_nop 0
	global_load_dwordx4 v[150:153], v[156:157], off offset:16
	s_waitcnt vmcnt(0)
	v_pk_add_f32 v[144:145], v[144:145], 1.0 op_sel_hi:[1,0]
	s_nop 0
	v_pk_mul_f32 v[136:137], v[136:137], v[144:145]
	v_pk_add_f32 v[146:147], v[146:147], 1.0 op_sel_hi:[1,0]
	v_div_scale_f32 v144, s[60:61], v136, v136, 1.0
	v_rcp_f32_e32 v145, v144
	v_pk_mul_f32 v[138:139], v[138:139], v[146:147]
	v_fma_f32 v146, -v144, v145, 1.0
	v_fmac_f32_e32 v145, v146, v145
	v_div_scale_f32 v146, vcc, 1.0, v136, 1.0
	v_mul_f32_e32 v147, v146, v145
	v_fma_f32 v158, -v144, v147, v146
	v_fmac_f32_e32 v147, v158, v145
	v_fma_f32 v144, -v144, v147, v146
	v_div_fmas_f32 v144, v144, v145, v147
	v_div_fixup_f32 v144, v144, v136, 1.0
	v_cmp_nlt_f32_e64 vcc, |v136|, s53
	v_div_scale_f32 v136, s[60:61], v137, v137, 1.0
	s_nop 0
	v_cndmask_b32_e32 v220, v253, v144, vcc
	v_rcp_f32_e32 v144, v136
	s_nop 0
	v_fma_f32 v145, -v136, v144, 1.0
	v_fmac_f32_e32 v144, v145, v144
	v_div_scale_f32 v145, vcc, 1.0, v137, 1.0
	v_mul_f32_e32 v146, v145, v144
	v_fma_f32 v147, -v136, v146, v145
	v_fmac_f32_e32 v146, v147, v144
	v_fma_f32 v136, -v136, v146, v145
	v_div_fmas_f32 v136, v136, v144, v146
	v_div_fixup_f32 v136, v136, v137, 1.0
	v_cmp_nlt_f32_e64 vcc, |v137|, s53
	s_nop 1
	v_cndmask_b32_e32 v221, v253, v136, vcc
	v_div_scale_f32 v136, s[60:61], v138, v138, 1.0
	v_rcp_f32_e32 v137, v136
	s_nop 0
	v_fma_f32 v144, -v136, v137, 1.0
	v_fmac_f32_e32 v137, v144, v137
	v_div_scale_f32 v144, vcc, 1.0, v138, 1.0
	v_mul_f32_e32 v145, v144, v137
	v_fma_f32 v146, -v136, v145, v144
	v_fmac_f32_e32 v145, v146, v137
	v_fma_f32 v136, -v136, v145, v144
	v_div_fmas_f32 v136, v136, v137, v145
	v_div_fixup_f32 v136, v136, v138, 1.0
	v_cmp_nlt_f32_e64 vcc, |v138|, s53
	s_nop 1
	v_cndmask_b32_e32 v222, v253, v136, vcc
	v_div_scale_f32 v136, s[60:61], v139, v139, 1.0
	v_rcp_f32_e32 v137, v136
	s_nop 0
	v_fma_f32 v138, -v136, v137, 1.0
	v_fmac_f32_e32 v137, v138, v137
	v_div_scale_f32 v138, vcc, 1.0, v139, 1.0
	v_mul_f32_e32 v144, v138, v137
	v_fma_f32 v145, -v136, v144, v138
	v_fmac_f32_e32 v144, v145, v137
	v_fma_f32 v136, -v136, v144, v138
	v_div_fmas_f32 v136, v136, v137, v144
	v_div_fixup_f32 v136, v136, v139, 1.0
	v_cmp_nlt_f32_e64 vcc, |v139|, s53
	v_pk_add_f32 v[138:139], v[150:151], 1.0 op_sel_hi:[1,0]
	s_nop 0
	v_pk_mul_f32 v[138:139], v[140:141], v[138:139]
	v_cndmask_b32_e32 v223, v253, v136, vcc
	v_div_scale_f32 v140, s[60:61], v138, v138, 1.0
	v_rcp_f32_e32 v141, v140
	v_pk_add_f32 v[136:137], v[152:153], 1.0 op_sel_hi:[1,0]
	s_nop 0
	v_pk_mul_f32 v[136:137], v[142:143], v[136:137]
	v_fma_f32 v142, -v140, v141, 1.0
	v_fmac_f32_e32 v141, v142, v141
	v_div_scale_f32 v142, vcc, 1.0, v138, 1.0
	v_mul_f32_e32 v143, v142, v141
	v_fma_f32 v144, -v140, v143, v142
	v_fmac_f32_e32 v143, v144, v141
	v_fma_f32 v140, -v140, v143, v142
	v_div_fmas_f32 v140, v140, v141, v143
	v_div_fixup_f32 v140, v140, v138, 1.0
	v_cmp_nlt_f32_e64 vcc, |v138|, s53
	v_div_scale_f32 v138, s[60:61], v139, v139, 1.0
	s_nop 0
	v_cndmask_b32_e32 v224, v253, v140, vcc
	v_rcp_f32_e32 v140, v138
	s_nop 0
	v_fma_f32 v141, -v138, v140, 1.0
	v_fmac_f32_e32 v140, v141, v140
	v_div_scale_f32 v141, vcc, 1.0, v139, 1.0
	v_mul_f32_e32 v142, v141, v140
	v_fma_f32 v143, -v138, v142, v141
	v_fmac_f32_e32 v142, v143, v140
	v_fma_f32 v138, -v138, v142, v141
	v_div_fmas_f32 v138, v138, v140, v142
	v_div_fixup_f32 v138, v138, v139, 1.0
	v_cmp_nlt_f32_e64 vcc, |v139|, s53
	s_nop 1
	v_cndmask_b32_e32 v225, v253, v138, vcc
	v_div_scale_f32 v138, s[60:61], v136, v136, 1.0
	v_rcp_f32_e32 v139, v138
	s_nop 0
	v_fma_f32 v140, -v138, v139, 1.0
	v_fmac_f32_e32 v139, v140, v139
	v_div_scale_f32 v140, vcc, 1.0, v136, 1.0
	v_mul_f32_e32 v141, v140, v139
	v_fma_f32 v142, -v138, v141, v140
	v_fmac_f32_e32 v141, v142, v139
	v_fma_f32 v138, -v138, v141, v140
	v_div_fmas_f32 v138, v138, v139, v141
	v_div_fixup_f32 v138, v138, v136, 1.0
	v_cmp_nlt_f32_e64 vcc, |v136|, s53
	v_div_scale_f32 v136, s[60:61], v137, v137, 1.0
	s_nop 0
	v_cndmask_b32_e32 v226, v253, v138, vcc
	v_rcp_f32_e32 v138, v136
	s_nop 0
	v_fma_f32 v139, -v136, v138, 1.0
	v_fmac_f32_e32 v138, v139, v138
	v_div_scale_f32 v139, vcc, 1.0, v137, 1.0
	v_mul_f32_e32 v140, v139, v138
	v_fma_f32 v141, -v136, v140, v139
	v_fmac_f32_e32 v140, v141, v138
	v_fma_f32 v136, -v136, v140, v139
	v_div_fmas_f32 v136, v136, v138, v140
	v_div_fixup_f32 v136, v136, v137, 1.0
	v_cmp_nlt_f32_e64 vcc, |v137|, s53
	s_nop 1
	v_cndmask_b32_e32 v227, v253, v136, vcc
	global_load_dwordx4 v[136:139], v[154:155], off offset:528
	global_load_dwordx4 v[140:143], v[154:155], off offset:512
	global_load_dwordx4 v[144:147], v[148:149], off offset:528
	s_nop 0
	global_load_dwordx4 v[152:155], v[148:149], off offset:512
	s_nop 0
	global_load_dwordx4 v[148:151], v[156:157], off offset:528
	s_nop 0
	global_load_dwordx4 v[156:159], v[156:157], off offset:512
	s_waitcnt vmcnt(1)
	v_pk_add_f32 v[148:149], v[148:149], 1.0 op_sel_hi:[1,0]
	s_waitcnt vmcnt(0)
	v_pk_add_f32 v[156:157], v[156:157], 1.0 op_sel_hi:[1,0]
	v_pk_add_f32 v[158:159], v[158:159], 1.0 op_sel_hi:[1,0]
	v_pk_mul_f32 v[152:153], v[152:153], v[156:157]
	v_pk_mul_f32 v[154:155], v[154:155], v[158:159]
	v_div_scale_f32 v156, s[60:61], v152, v152, 1.0
	v_rcp_f32_e32 v157, v156
	v_pk_mul_f32 v[144:145], v[144:145], v[148:149]
	v_pk_add_f32 v[150:151], v[150:151], 1.0 op_sel_hi:[1,0]
	v_div_scale_f32 v148, s[60:61], v144, v144, 1.0
	v_fma_f32 v158, -v156, v157, 1.0
	v_fmac_f32_e32 v157, v158, v157
	v_div_scale_f32 v158, vcc, 1.0, v152, 1.0
	v_mul_f32_e32 v159, v158, v157
	v_fma_f32 v254, -v156, v159, v158
	v_fmac_f32_e32 v159, v254, v157
	v_fma_f32 v156, -v156, v159, v158
	v_div_fmas_f32 v156, v156, v157, v159
	v_div_fixup_f32 v156, v156, v152, 1.0
	v_cmp_nlt_f32_e64 vcc, |v152|, s53
	v_div_scale_f32 v152, s[60:61], v153, v153, 1.0
	s_nop 0
	v_cndmask_b32_e32 v230, v253, v156, vcc
	v_rcp_f32_e32 v156, v152
	v_rcp_f32_e32 v149, v148
	v_pk_mul_f32 v[146:147], v[146:147], v[150:151]
	v_fma_f32 v157, -v152, v156, 1.0
	v_fmac_f32_e32 v156, v157, v156
	v_div_scale_f32 v157, vcc, 1.0, v153, 1.0
	v_mul_f32_e32 v158, v157, v156
	v_fma_f32 v159, -v152, v158, v157
	v_fmac_f32_e32 v158, v159, v156
	v_fma_f32 v152, -v152, v158, v157
	v_div_fmas_f32 v152, v152, v156, v158
	v_div_fixup_f32 v152, v152, v153, 1.0
	v_cmp_nlt_f32_e64 vcc, |v153|, s53
	v_fma_f32 v150, -v148, v149, 1.0
	v_fmac_f32_e32 v149, v150, v149
	v_cndmask_b32_e32 v231, v253, v152, vcc
	v_div_scale_f32 v152, s[60:61], v154, v154, 1.0
	v_rcp_f32_e32 v153, v152
	s_nop 0
	v_fma_f32 v156, -v152, v153, 1.0
	v_fmac_f32_e32 v153, v156, v153
	v_div_scale_f32 v156, vcc, 1.0, v154, 1.0
	v_mul_f32_e32 v157, v156, v153
	v_fma_f32 v158, -v152, v157, v156
	v_fmac_f32_e32 v157, v158, v153
	v_fma_f32 v152, -v152, v157, v156
	v_div_fmas_f32 v152, v152, v153, v157
	v_div_fixup_f32 v152, v152, v154, 1.0
	v_cmp_nlt_f32_e64 vcc, |v154|, s53
	s_nop 1
	v_cndmask_b32_e32 v232, v253, v152, vcc
	v_div_scale_f32 v152, s[60:61], v155, v155, 1.0
	v_rcp_f32_e32 v153, v152
	s_nop 0
	v_fma_f32 v154, -v152, v153, 1.0
	v_fmac_f32_e32 v153, v154, v153
	v_div_scale_f32 v154, vcc, 1.0, v155, 1.0
	v_mul_f32_e32 v156, v154, v153
	v_fma_f32 v157, -v152, v156, v154
	v_fmac_f32_e32 v156, v157, v153
	v_fma_f32 v152, -v152, v156, v154
	v_div_fmas_f32 v152, v152, v153, v156
	v_div_fixup_f32 v152, v152, v155, 1.0
	v_cmp_nlt_f32_e64 vcc, |v155|, s53
	s_nop 1
	v_cndmask_b32_e32 v233, v253, v152, vcc
	v_div_scale_f32 v150, vcc, 1.0, v144, 1.0
	v_mul_f32_e32 v151, v150, v149
	v_fma_f32 v152, -v148, v151, v150
	v_fmac_f32_e32 v151, v152, v149
	v_fma_f32 v148, -v148, v151, v150
	v_div_fmas_f32 v148, v148, v149, v151
	v_div_fixup_f32 v148, v148, v144, 1.0
	v_cmp_nlt_f32_e64 vcc, |v144|, s53
	v_div_scale_f32 v144, s[60:61], v145, v145, 1.0
	s_nop 0
	v_cndmask_b32_e32 v234, v253, v148, vcc
	v_rcp_f32_e32 v148, v144
	s_nop 0
	v_fma_f32 v149, -v144, v148, 1.0
	v_fmac_f32_e32 v148, v149, v148
	v_div_scale_f32 v149, vcc, 1.0, v145, 1.0
	v_mul_f32_e32 v150, v149, v148
	v_fma_f32 v151, -v144, v150, v149
	v_fmac_f32_e32 v150, v151, v148
	v_fma_f32 v144, -v144, v150, v149
	v_div_fmas_f32 v144, v144, v148, v150
	v_div_fixup_f32 v144, v144, v145, 1.0
	v_cmp_nlt_f32_e64 vcc, |v145|, s53
	s_nop 1
	v_cndmask_b32_e32 v235, v253, v144, vcc
	v_div_scale_f32 v144, s[60:61], v146, v146, 1.0
	v_rcp_f32_e32 v145, v144
	s_nop 0
	v_fma_f32 v148, -v144, v145, 1.0
	v_fmac_f32_e32 v145, v148, v145
	v_div_scale_f32 v148, vcc, 1.0, v146, 1.0
	v_mul_f32_e32 v149, v148, v145
	v_fma_f32 v150, -v144, v149, v148
	v_fmac_f32_e32 v149, v150, v145
	v_fma_f32 v144, -v144, v149, v148
	v_div_fmas_f32 v144, v144, v145, v149
	v_div_fixup_f32 v144, v144, v146, 1.0
	v_cmp_nlt_f32_e64 vcc, |v146|, s53
	s_nop 1
	v_cndmask_b32_e32 v236, v253, v144, vcc
	v_div_scale_f32 v144, s[60:61], v147, v147, 1.0
	v_rcp_f32_e32 v145, v144
	s_nop 0
	v_fma_f32 v146, -v144, v145, 1.0
	v_fmac_f32_e32 v145, v146, v145
	v_div_scale_f32 v146, vcc, 1.0, v147, 1.0
	v_mul_f32_e32 v148, v146, v145
	v_fma_f32 v149, -v144, v148, v146
	v_fmac_f32_e32 v148, v149, v145
	v_fma_f32 v144, -v144, v148, v146
	v_div_fmas_f32 v144, v144, v145, v148
	v_div_fixup_f32 v144, v144, v147, 1.0
	v_cmp_nlt_f32_e64 vcc, |v147|, s53
	s_nop 1
	v_cndmask_b32_e32 v237, v253, v144, vcc
	v_lshl_add_u64 v[240:241], s[4:5], 0, v[228:229]
	v_lshlrev_b64 v[228:229], 12, v[242:243]
	s_waitcnt vmcnt(15)
	v_lshlrev_b32_e32 v242, 16, v204
	v_and_b32_e32 v243, 0xffff0000, v204
	v_lshlrev_b32_e32 v204, 16, v205
	v_and_b32_e32 v205, 0xffff0000, v205
	v_pk_mul_f32 v[204:205], v[222:223], v[204:205]
	v_pk_mul_f32 v[242:243], v[220:221], v[242:243]
	v_lshl_add_u64 v[228:229], v[240:241], 0, v[228:229]
	v_lshlrev_b32_e32 v250, 16, v206
	v_and_b32_e32 v251, 0xffff0000, v206
	v_lshlrev_b32_e32 v206, 16, v207
	v_and_b32_e32 v207, 0xffff0000, v207
	v_pk_fma_f32 v[126:127], v[126:127], v[134:135], v[204:205]
	v_pk_fma_f32 v[124:125], v[124:125], v[132:133], v[242:243]
	global_store_dwordx4 v[228:229], v[124:127], off
	s_mov_b64 s[4:5], -1
	s_nop 0
	v_pk_mul_f32 v[124:125], v[226:227], v[206:207]
	v_pk_mul_f32 v[126:127], v[224:225], v[250:251]
	v_pk_fma_f32 v[122:123], v[122:123], v[130:131], v[124:125]
	v_pk_fma_f32 v[120:121], v[120:121], v[128:129], v[126:127]
	global_store_dwordx4 v[228:229], v[120:123], off offset:16
	s_waitcnt vmcnt(16)
	v_lshlrev_b32_e32 v124, 16, v202
	v_and_b32_e32 v125, 0xffff0000, v202
	v_lshlrev_b32_e32 v120, 16, v200
	v_and_b32_e32 v121, 0xffff0000, v200
	v_lshlrev_b32_e32 v122, 16, v201
	v_and_b32_e32 v123, 0xffff0000, v201
	v_pk_mul_f32 v[122:123], v[232:233], v[122:123]
	v_pk_mul_f32 v[120:121], v[230:231], v[120:121]
	v_lshlrev_b32_e32 v126, 16, v203
	v_and_b32_e32 v127, 0xffff0000, v203
	v_pk_fma_f32 v[118:119], v[118:119], v[142:143], v[122:123]
	v_pk_fma_f32 v[116:117], v[116:117], v[140:141], v[120:121]
	global_store_dwordx4 v[228:229], v[116:119], off offset:512
	s_nop 1
	v_pk_mul_f32 v[116:117], v[236:237], v[126:127]
	v_pk_mul_f32 v[118:119], v[234:235], v[124:125]
	v_pk_fma_f32 v[110:111], v[110:111], v[138:139], v[116:117]
	v_pk_fma_f32 v[108:109], v[108:109], v[136:137], v[118:119]
	global_store_dwordx4 v[228:229], v[108:111], off offset:528
	s_waitcnt vmcnt(17)
	v_lshlrev_b32_e32 v116, 16, v198
	v_and_b32_e32 v117, 0xffff0000, v198
	v_lshlrev_b32_e32 v108, 16, v196
	v_and_b32_e32 v109, 0xffff0000, v196
	v_lshlrev_b32_e32 v110, 16, v197
	v_and_b32_e32 v111, 0xffff0000, v197
	v_pk_mul_f32 v[108:109], v[220:221], v[108:109]
	v_pk_mul_f32 v[110:111], v[222:223], v[110:111]
	v_pk_fma_f32 v[108:109], v[112:113], v[132:133], v[108:109]
	v_add_co_u32_e32 v112, vcc, s41, v228
	v_lshlrev_b32_e32 v118, 16, v199
	v_and_b32_e32 v119, 0xffff0000, v199
	v_pk_fma_f32 v[110:111], v[114:115], v[134:135], v[110:111]
	v_addc_co_u32_e32 v113, vcc, 0, v229, vcc
	global_store_dwordx4 v[112:113], v[108:111], off
	s_nop 1
	v_pk_mul_f32 v[108:109], v[226:227], v[118:119]
	v_pk_mul_f32 v[110:111], v[224:225], v[116:117]
	v_pk_fma_f32 v[106:107], v[106:107], v[130:131], v[108:109]
	v_pk_fma_f32 v[104:105], v[104:105], v[128:129], v[110:111]
	global_store_dwordx4 v[112:113], v[104:107], off offset:16
	s_waitcnt vmcnt(18)
	v_lshlrev_b32_e32 v108, 16, v194
	v_and_b32_e32 v109, 0xffff0000, v194
	v_lshlrev_b32_e32 v104, 16, v192
	v_and_b32_e32 v105, 0xffff0000, v192
	v_lshlrev_b32_e32 v106, 16, v193
	v_and_b32_e32 v107, 0xffff0000, v193
	v_pk_mul_f32 v[106:107], v[232:233], v[106:107]
	v_pk_mul_f32 v[104:105], v[230:231], v[104:105]
	v_lshlrev_b32_e32 v110, 16, v195
	v_and_b32_e32 v111, 0xffff0000, v195
	v_pk_fma_f32 v[102:103], v[102:103], v[142:143], v[106:107]
	v_pk_fma_f32 v[100:101], v[100:101], v[140:141], v[104:105]
	global_store_dwordx4 v[112:113], v[100:103], off offset:512
	s_nop 1
	v_pk_mul_f32 v[100:101], v[236:237], v[110:111]
	v_pk_mul_f32 v[102:103], v[234:235], v[108:109]
	v_pk_fma_f32 v[94:95], v[94:95], v[138:139], v[100:101]
	v_pk_fma_f32 v[92:93], v[92:93], v[136:137], v[102:103]
	global_store_dwordx4 v[112:113], v[92:95], off offset:528
	s_waitcnt vmcnt(19)
	v_lshlrev_b32_e32 v100, 16, v190
	v_and_b32_e32 v101, 0xffff0000, v190
	v_lshlrev_b32_e32 v92, 16, v188
	v_and_b32_e32 v93, 0xffff0000, v188
	v_lshlrev_b32_e32 v94, 16, v189
	v_and_b32_e32 v95, 0xffff0000, v189
	v_pk_mul_f32 v[92:93], v[220:221], v[92:93]
	v_pk_mul_f32 v[94:95], v[222:223], v[94:95]
	v_pk_fma_f32 v[92:93], v[96:97], v[132:133], v[92:93]
	v_add_co_u32_e32 v96, vcc, s54, v228
	v_lshlrev_b32_e32 v102, 16, v191
	v_and_b32_e32 v103, 0xffff0000, v191
	v_pk_fma_f32 v[94:95], v[98:99], v[134:135], v[94:95]
	v_addc_co_u32_e32 v97, vcc, 0, v229, vcc
	global_store_dwordx4 v[96:97], v[92:95], off
	s_nop 1
	v_pk_mul_f32 v[92:93], v[226:227], v[102:103]
	v_pk_mul_f32 v[94:95], v[224:225], v[100:101]
	v_pk_fma_f32 v[90:91], v[90:91], v[130:131], v[92:93]
	v_pk_fma_f32 v[88:89], v[88:89], v[128:129], v[94:95]
	global_store_dwordx4 v[96:97], v[88:91], off offset:16
	s_waitcnt vmcnt(20)
	v_lshlrev_b32_e32 v92, 16, v186
	v_and_b32_e32 v93, 0xffff0000, v186
	v_lshlrev_b32_e32 v88, 16, v184
	v_and_b32_e32 v89, 0xffff0000, v184
	v_lshlrev_b32_e32 v90, 16, v185
	v_and_b32_e32 v91, 0xffff0000, v185
	v_pk_mul_f32 v[90:91], v[232:233], v[90:91]
	v_pk_mul_f32 v[88:89], v[230:231], v[88:89]
	v_lshlrev_b32_e32 v94, 16, v187
	v_and_b32_e32 v95, 0xffff0000, v187
	v_pk_fma_f32 v[86:87], v[86:87], v[142:143], v[90:91]
	v_pk_fma_f32 v[84:85], v[84:85], v[140:141], v[88:89]
	global_store_dwordx4 v[96:97], v[84:87], off offset:512
	s_nop 1
	v_pk_mul_f32 v[84:85], v[236:237], v[94:95]
	v_pk_mul_f32 v[86:87], v[234:235], v[92:93]
	v_pk_fma_f32 v[78:79], v[78:79], v[138:139], v[84:85]
	v_pk_fma_f32 v[76:77], v[76:77], v[136:137], v[86:87]
	global_store_dwordx4 v[96:97], v[76:79], off offset:528
	s_waitcnt vmcnt(21)
	v_lshlrev_b32_e32 v84, 16, v182
	v_and_b32_e32 v85, 0xffff0000, v182
	v_lshlrev_b32_e32 v76, 16, v180
	v_and_b32_e32 v77, 0xffff0000, v180
	v_lshlrev_b32_e32 v78, 16, v181
	v_and_b32_e32 v79, 0xffff0000, v181
	v_pk_mul_f32 v[76:77], v[220:221], v[76:77]
	v_pk_mul_f32 v[78:79], v[222:223], v[78:79]
	v_pk_fma_f32 v[76:77], v[80:81], v[132:133], v[76:77]
	v_add_co_u32_e32 v80, vcc, s55, v228
	v_lshlrev_b32_e32 v86, 16, v183
	v_and_b32_e32 v87, 0xffff0000, v183
	v_pk_fma_f32 v[78:79], v[82:83], v[134:135], v[78:79]
	v_addc_co_u32_e32 v81, vcc, 0, v229, vcc
	global_store_dwordx4 v[80:81], v[76:79], off
	s_nop 1
	v_pk_mul_f32 v[76:77], v[226:227], v[86:87]
	v_pk_mul_f32 v[78:79], v[224:225], v[84:85]
	v_pk_fma_f32 v[74:75], v[74:75], v[130:131], v[76:77]
	v_pk_fma_f32 v[72:73], v[72:73], v[128:129], v[78:79]
	global_store_dwordx4 v[80:81], v[72:75], off offset:16
	s_waitcnt vmcnt(22)
	v_lshlrev_b32_e32 v76, 16, v178
	v_and_b32_e32 v77, 0xffff0000, v178
	v_lshlrev_b32_e32 v72, 16, v176
	v_and_b32_e32 v73, 0xffff0000, v176
	v_lshlrev_b32_e32 v74, 16, v177
	v_and_b32_e32 v75, 0xffff0000, v177
	v_pk_mul_f32 v[74:75], v[232:233], v[74:75]
	v_pk_mul_f32 v[72:73], v[230:231], v[72:73]
	v_lshlrev_b32_e32 v78, 16, v179
	v_and_b32_e32 v79, 0xffff0000, v179
	v_pk_fma_f32 v[70:71], v[70:71], v[142:143], v[74:75]
	v_pk_fma_f32 v[68:69], v[68:69], v[140:141], v[72:73]
	global_store_dwordx4 v[80:81], v[68:71], off offset:512
	s_waitcnt vmcnt(22)
	v_lshlrev_b32_e32 v72, 16, v175
	v_and_b32_e32 v73, 0xffff0000, v175
	v_pk_mul_f32 v[68:69], v[236:237], v[78:79]
	v_pk_mul_f32 v[70:71], v[234:235], v[76:77]
	v_pk_fma_f32 v[66:67], v[66:67], v[138:139], v[68:69]
	v_pk_fma_f32 v[64:65], v[64:65], v[136:137], v[70:71]
	global_store_dwordx4 v[80:81], v[64:67], off offset:528
	v_lshlrev_b32_e32 v68, 16, v173
	v_and_b32_e32 v69, 0xffff0000, v173
	v_lshlrev_b32_e32 v66, 16, v172
	v_and_b32_e32 v67, 0xffff0000, v172
	v_lshlrev_b64 v[64:65], 12, v[238:239]
	v_pk_mul_f32 v[68:69], v[222:223], v[68:69]
	v_pk_mul_f32 v[66:67], v[220:221], v[66:67]
	v_lshl_add_u64 v[64:65], v[240:241], 0, v[64:65]
	v_lshlrev_b32_e32 v70, 16, v174
	v_and_b32_e32 v71, 0xffff0000, v174
	v_pk_fma_f32 v[62:63], v[62:63], v[134:135], v[68:69]
	v_pk_fma_f32 v[60:61], v[60:61], v[132:133], v[66:67]
	global_store_dwordx4 v[64:65], v[60:63], off
	s_nop 1
	v_pk_mul_f32 v[60:61], v[226:227], v[72:73]
	v_pk_mul_f32 v[62:63], v[224:225], v[70:71]
	v_pk_fma_f32 v[58:59], v[58:59], v[130:131], v[60:61]
	v_pk_fma_f32 v[56:57], v[56:57], v[128:129], v[62:63]
	global_store_dwordx4 v[64:65], v[56:59], off offset:16
	s_waitcnt vmcnt(24)
	v_lshlrev_b32_e32 v60, 16, v170
	v_and_b32_e32 v61, 0xffff0000, v170
	v_lshlrev_b32_e32 v56, 16, v168
	v_and_b32_e32 v57, 0xffff0000, v168
	v_lshlrev_b32_e32 v58, 16, v169
	v_and_b32_e32 v59, 0xffff0000, v169
	v_pk_mul_f32 v[58:59], v[232:233], v[58:59]
	v_pk_mul_f32 v[56:57], v[230:231], v[56:57]
	v_lshlrev_b32_e32 v62, 16, v171
	v_and_b32_e32 v63, 0xffff0000, v171
	v_pk_fma_f32 v[54:55], v[54:55], v[142:143], v[58:59]
	v_pk_fma_f32 v[52:53], v[52:53], v[140:141], v[56:57]
	global_store_dwordx4 v[64:65], v[52:55], off offset:512
	s_nop 1
	v_pk_mul_f32 v[52:53], v[236:237], v[62:63]
	v_pk_mul_f32 v[54:55], v[234:235], v[60:61]
	v_pk_fma_f32 v[46:47], v[46:47], v[138:139], v[52:53]
	v_pk_fma_f32 v[44:45], v[44:45], v[136:137], v[54:55]
	global_store_dwordx4 v[64:65], v[44:47], off offset:528
	s_waitcnt vmcnt(25)
	v_lshlrev_b32_e32 v52, 16, v166
	v_and_b32_e32 v53, 0xffff0000, v166
	v_lshlrev_b32_e32 v44, 16, v164
	v_and_b32_e32 v45, 0xffff0000, v164
	v_lshlrev_b32_e32 v46, 16, v165
	v_and_b32_e32 v47, 0xffff0000, v165
	v_pk_mul_f32 v[44:45], v[220:221], v[44:45]
	v_pk_mul_f32 v[46:47], v[222:223], v[46:47]
	v_pk_fma_f32 v[44:45], v[48:49], v[132:133], v[44:45]
	v_add_co_u32_e32 v48, vcc, s56, v228
	v_lshlrev_b32_e32 v54, 16, v167
	v_and_b32_e32 v55, 0xffff0000, v167
	v_pk_fma_f32 v[46:47], v[50:51], v[134:135], v[46:47]
	v_addc_co_u32_e32 v49, vcc, 0, v229, vcc
	global_store_dwordx4 v[48:49], v[44:47], off
	s_nop 1
	v_pk_mul_f32 v[44:45], v[226:227], v[54:55]
	v_pk_mul_f32 v[46:47], v[224:225], v[52:53]
	v_pk_fma_f32 v[42:43], v[42:43], v[130:131], v[44:45]
	v_pk_fma_f32 v[40:41], v[40:41], v[128:129], v[46:47]
	global_store_dwordx4 v[48:49], v[40:43], off offset:16
	s_waitcnt vmcnt(26)
	v_lshlrev_b32_e32 v44, 16, v162
	v_and_b32_e32 v45, 0xffff0000, v162
	v_lshlrev_b32_e32 v40, 16, v160
	v_and_b32_e32 v41, 0xffff0000, v160
	v_lshlrev_b32_e32 v42, 16, v161
	v_and_b32_e32 v43, 0xffff0000, v161
	v_pk_mul_f32 v[42:43], v[232:233], v[42:43]
	v_pk_mul_f32 v[40:41], v[230:231], v[40:41]
	v_lshlrev_b32_e32 v46, 16, v163
	v_and_b32_e32 v47, 0xffff0000, v163
	v_pk_fma_f32 v[38:39], v[38:39], v[142:143], v[42:43]
	v_pk_fma_f32 v[36:37], v[36:37], v[140:141], v[40:41]
	global_store_dwordx4 v[48:49], v[36:39], off offset:512
	s_nop 1
	v_pk_mul_f32 v[36:37], v[236:237], v[46:47]
	v_pk_mul_f32 v[38:39], v[234:235], v[44:45]
	v_pk_fma_f32 v[30:31], v[30:31], v[138:139], v[36:37]
	v_pk_fma_f32 v[28:29], v[28:29], v[136:137], v[38:39]
	global_store_dwordx4 v[48:49], v[28:31], off offset:528
	s_waitcnt vmcnt(27)
	v_lshlrev_b32_e32 v36, 16, v210
	v_and_b32_e32 v37, 0xffff0000, v210
	v_lshlrev_b32_e32 v28, 16, v208
	v_and_b32_e32 v29, 0xffff0000, v208
	v_lshlrev_b32_e32 v30, 16, v209
	v_and_b32_e32 v31, 0xffff0000, v209
	v_pk_mul_f32 v[28:29], v[220:221], v[28:29]
	v_pk_mul_f32 v[30:31], v[222:223], v[30:31]
	v_pk_fma_f32 v[28:29], v[32:33], v[132:133], v[28:29]
	v_add_co_u32_e32 v32, vcc, s57, v228
	v_lshlrev_b32_e32 v38, 16, v211
	v_and_b32_e32 v39, 0xffff0000, v211
	v_pk_fma_f32 v[30:31], v[34:35], v[134:135], v[30:31]
	v_addc_co_u32_e32 v33, vcc, 0, v229, vcc
	global_store_dwordx4 v[32:33], v[28:31], off
	s_nop 1
	v_pk_mul_f32 v[28:29], v[226:227], v[38:39]
	v_pk_mul_f32 v[30:31], v[224:225], v[36:37]
	v_pk_fma_f32 v[26:27], v[26:27], v[130:131], v[28:29]
	v_pk_fma_f32 v[24:25], v[24:25], v[128:129], v[30:31]
	global_store_dwordx4 v[32:33], v[24:27], off offset:16
	s_waitcnt vmcnt(28)
	v_lshlrev_b32_e32 v28, 16, v214
	v_and_b32_e32 v29, 0xffff0000, v214
	v_lshlrev_b32_e32 v24, 16, v212
	v_and_b32_e32 v25, 0xffff0000, v212
	v_lshlrev_b32_e32 v26, 16, v213
	v_and_b32_e32 v27, 0xffff0000, v213
	v_pk_mul_f32 v[26:27], v[232:233], v[26:27]
	v_pk_mul_f32 v[24:25], v[230:231], v[24:25]
	v_lshlrev_b32_e32 v30, 16, v215
	v_and_b32_e32 v31, 0xffff0000, v215
	v_pk_fma_f32 v[22:23], v[22:23], v[142:143], v[26:27]
	v_pk_fma_f32 v[20:21], v[20:21], v[140:141], v[24:25]
	global_store_dwordx4 v[32:33], v[20:23], off offset:512
	s_nop 1
	v_pk_mul_f32 v[20:21], v[236:237], v[30:31]
	v_pk_mul_f32 v[22:23], v[234:235], v[28:29]
	v_pk_fma_f32 v[14:15], v[14:15], v[138:139], v[20:21]
	v_pk_fma_f32 v[12:13], v[12:13], v[136:137], v[22:23]
	global_store_dwordx4 v[32:33], v[12:15], off offset:528
	s_waitcnt vmcnt(29)
	v_lshlrev_b32_e32 v20, 16, v218
	v_and_b32_e32 v21, 0xffff0000, v218
	v_lshlrev_b32_e32 v12, 16, v216
	v_and_b32_e32 v13, 0xffff0000, v216
	v_lshlrev_b32_e32 v14, 16, v217
	v_and_b32_e32 v15, 0xffff0000, v217
	v_pk_mul_f32 v[12:13], v[220:221], v[12:13]
	v_pk_mul_f32 v[14:15], v[222:223], v[14:15]
	v_pk_fma_f32 v[12:13], v[16:17], v[132:133], v[12:13]
	v_add_co_u32_e32 v16, vcc, s58, v228
	v_lshlrev_b32_e32 v22, 16, v219
	v_and_b32_e32 v23, 0xffff0000, v219
	v_pk_fma_f32 v[14:15], v[18:19], v[134:135], v[14:15]
	v_addc_co_u32_e32 v17, vcc, 0, v229, vcc
	global_store_dwordx4 v[16:17], v[12:15], off
	s_andn2_b64 vcc, exec, s[28:29]
	s_nop 0
	v_pk_mul_f32 v[12:13], v[226:227], v[22:23]
	v_pk_mul_f32 v[14:15], v[224:225], v[20:21]
	v_pk_fma_f32 v[10:11], v[10:11], v[130:131], v[12:13]
	v_pk_fma_f32 v[8:9], v[8:9], v[128:129], v[14:15]
	global_store_dwordx4 v[16:17], v[8:11], off offset:16
	s_waitcnt vmcnt(30)
	v_lshlrev_b32_e32 v12, 16, v248
	v_and_b32_e32 v13, 0xffff0000, v248
	v_lshlrev_b32_e32 v8, 16, v246
	v_and_b32_e32 v9, 0xffff0000, v246
	v_lshlrev_b32_e32 v10, 16, v247
	v_and_b32_e32 v11, 0xffff0000, v247
	v_pk_mul_f32 v[10:11], v[232:233], v[10:11]
	v_pk_mul_f32 v[8:9], v[230:231], v[8:9]
	v_lshlrev_b32_e32 v14, 16, v249
	v_and_b32_e32 v15, 0xffff0000, v249
	v_pk_fma_f32 v[6:7], v[6:7], v[142:143], v[10:11]
	v_pk_fma_f32 v[4:5], v[4:5], v[140:141], v[8:9]
	global_store_dwordx4 v[16:17], v[4:7], off offset:512
	s_nop 1
	v_pk_mul_f32 v[4:5], v[236:237], v[14:15]
	v_pk_mul_f32 v[6:7], v[234:235], v[12:13]
	v_pk_fma_f32 v[2:3], v[2:3], v[138:139], v[4:5]
	v_pk_fma_f32 v[0:1], v[0:1], v[136:137], v[6:7]
	global_store_dwordx4 v[16:17], v[0:3], off offset:528
	s_cbranch_vccnz .LBB0_1515
	s_andn2_b64 vcc, exec, s[8:9]
	s_cbranch_vccnz .LBB0_1514
	s_barrier
	s_branch .LBB0_1514

	.amdhsa_kernel _Z6mk_fwd4Args
		.amdhsa_group_segment_fixed_size 0
		.amdhsa_private_segment_fixed_size 0
		.amdhsa_kernarg_size 448
		.amdhsa_user_sgpr_count 2
		.amdhsa_user_sgpr_dispatch_ptr 0
		.amdhsa_user_sgpr_queue_ptr 0
		.amdhsa_user_sgpr_kernarg_segment_ptr 1
		.amdhsa_user_sgpr_dispatch_id 0
		.amdhsa_user_sgpr_kernarg_preload_length 0
		.amdhsa_user_sgpr_kernarg_preload_offset 0
		.amdhsa_user_sgpr_private_segment_size 0
		.amdhsa_uses_dynamic_stack 0
		.amdhsa_enable_private_segment 0
		.amdhsa_system_sgpr_workgroup_id_x 1
		.amdhsa_system_sgpr_workgroup_id_y 0
		.amdhsa_system_sgpr_workgroup_id_z 0
		.amdhsa_system_sgpr_workgroup_info 0
		.amdhsa_system_vgpr_workitem_id 0
		.amdhsa_next_free_vgpr 256
		.amdhsa_next_free_sgpr 98
		.amdhsa_accum_offset 256
		.amdhsa_reserve_vcc 1
		.amdhsa_float_round_mode_32 0
		.amdhsa_float_round_mode_16_64 0
		.amdhsa_float_denorm_mode_32 3
		.amdhsa_float_denorm_mode_16_64 3
		.amdhsa_dx10_clamp 1
		.amdhsa_ieee_mode 1
		.amdhsa_fp16_overflow 0
		.amdhsa_tg_split 0
		.amdhsa_exception_fp_ieee_invalid_op 0
		.amdhsa_exception_fp_denorm_src 0
		.amdhsa_exception_fp_ieee_div_zero 0
		.amdhsa_exception_fp_ieee_overflow 0
		.amdhsa_exception_fp_ieee_underflow 0
		.amdhsa_exception_fp_ieee_inexact 0
		.amdhsa_exception_int_div_zero 0
	.end_amdhsa_kernel

amdhsa.kernels:
  - .agpr_count:     0
    .args:
      - .offset:         0
        .size:           192
        .value_kind:     by_value
      - .offset:         192
        .size:           4
        .value_kind:     hidden_block_count_x
      - .offset:         196
        .size:           4
        .value_kind:     hidden_block_count_y
      - .offset:         200
        .size:           4
        .value_kind:     hidden_block_count_z
      - .offset:         204
        .size:           2
        .value_kind:     hidden_group_size_x
      - .offset:         206
        .size:           2
        .value_kind:     hidden_group_size_y
      - .offset:         208
        .size:           2
        .value_kind:     hidden_group_size_z
      - .offset:         210
        .size:           2
        .value_kind:     hidden_remainder_x
      - .offset:         212
        .size:           2
        .value_kind:     hidden_remainder_y
      - .offset:         214
        .size:           2
        .value_kind:     hidden_remainder_z
      - .offset:         232
        .size:           8
        .value_kind:     hidden_global_offset_x
      - .offset:         240
        .size:           8
        .value_kind:     hidden_global_offset_y
      - .offset:         248
        .size:           8
        .value_kind:     hidden_global_offset_z
      - .offset:         256
        .size:           2
        .value_kind:     hidden_grid_dims
      - .offset:         312
        .size:           4
        .value_kind:     hidden_dynamic_lds_size
    .group_segment_fixed_size: 0
    .kernarg_segment_align: 8
    .kernarg_segment_size: 448
    .language:       OpenCL C
    .language_version:
      - 2
      - 0
    .max_flat_workgroup_size: 512
    .name:           _Z6mk_fwd4Args
    .private_segment_fixed_size: 0
    .sgpr_count:     104
    .sgpr_spill_count: 9
    .symbol:         _Z6mk_fwd4Args.kd
    .uniform_work_group_size: 1
    .uses_dynamic_stack: false
    .vgpr_count:     256
    .vgpr_spill_count: 0
    .wavefront_size: 64
